# MLA attention: half-tile software pipeline as in diff (K LDS window shifted 32 keys, rescale check per 32 keys)
# speedup vs baseline: 1.0519x; 1.0124x over previous
.LBB0_657:
	s_add_i32 s2, s14, s55
	s_cmpk_gt_i32 s2, 0x7ff
	s_mov_b64 s[0:1], -1
	s_cbranch_scc1 .LBB0_656
	s_ashr_i32 s4, s2, 8
	s_bfe_u32 s19, s2, 0x40004
	v_mov_b32_e32 v0, v194
	s_ashr_i32 s5, s4, 31
	s_lshl_b32 s2, s2, 8
	s_lshl_b64 s[0:1], s[4:5], 12
	s_and_b32 s2, s2, 0xf00
	v_ashrrev_i32_e32 v2, 1, v0
	s_or_b32 s0, s0, s2
	v_and_b32_e32 v2, 0xffffffe0, v2
	v_ashrrev_i32_e32 v3, 31, v2
	v_and_or_b32 v4, v0, 31, s0
	v_mov_b32_e32 v5, s1
	v_lshl_add_u64 v[126:127], v[4:5], 0, v[2:3]
	v_mov_b64_e32 v[2:3], s[56:57]
	s_movk_i32 s2, 0xc00
	v_mad_u64_u32 v[2:3], s[0:1], v126, s2, v[2:3]
	v_bfe_u32 v132, v0, 5, 1
	v_mad_i32_i24 v3, v127, s2, v3
	s_mul_i32 s90, s19, 0xc0
	s_lshl_b64 s[0:1], s[4:5], 24
	s_lshl_b64 s[6:7], s[4:5], 18
	v_readlane_b32 s2, v254, 61
	v_lshl_add_u64 v[2:3], v[2:3], 0, s[90:91]
	v_lshlrev_b32_e32 v0, 4, v132
	v_readlane_b32 s3, v254, 62
	s_add_u32 s8, s2, s6
	v_lshl_add_u64 v[2:3], v[2:3], 0, v[0:1]
	s_addc_u32 s9, s3, s7
	global_load_dwordx4 v[82:85], v[2:3], off
	global_load_dwordx4 v[86:89], v[2:3], off offset:32
	global_load_dwordx4 v[90:93], v[2:3], off offset:64
	global_load_dwordx4 v[94:97], v[2:3], off offset:96
	global_load_dwordx4 v[98:101], v[2:3], off offset:128
	global_load_dwordx4 v[102:105], v[2:3], off offset:160
	s_add_u32 s2, s58, s0
	v_mov_b32_e32 v14, v194
	s_addc_u32 s3, s59, s1
	s_lshl_b32 s4, s19, 8
	s_add_u32 s10, s2, s4
	v_ashrrev_i32_e32 v11, 2, v14
	v_lshlrev_b32_e32 v10, 4, v14
	v_and_b32_e32 v133, 0x70, v10
	v_lshlrev_b32_e32 v0, 11, v11
	s_movk_i32 s2, 0xf000
	s_addc_u32 s11, s3, 0
	v_and_or_b32 v0, v0, s2, v133
	v_add_u32_e32 v241, 0x20000, v0
	global_load_dwordx4 v[2:5], v241, s[10:11]
	s_mov_b32 s100, 0xfffe0000
	s_mov_b32 s101, -1
	v_lshl_add_u64 v[246:247], s[10:11], 0, v[0:1]
	v_lshl_add_u64 v[246:247], v[246:247], 0, s[100:101]
	global_load_dwordx4 v[248:251], v[246:247], off
	s_movk_i32 s2, 0xff
	v_cmp_lt_i32_e64 s[4:5], s2, v14
	s_movk_i32 s2, 0x100
	v_cmp_gt_i32_e64 s[2:3], s2, v14
	s_and_saveexec_b64 s[16:17], s[2:3]
	s_cbranch_execz .LBB0_660
	v_add_u32_e32 v244, 0x800, v10
	global_load_dwordx4 v[106:109], v244, s[8:9]
	v_mov_b32_e32 v252, v10
	v_mov_b32_e32 v253, 0
	v_lshl_add_u64 v[252:253], s[8:9], 0, v[252:253]
	s_mov_b32 s98, 0xfffff800
	s_mov_b32 s99, -1
	v_lshl_add_u64 v[252:253], v[252:253], 0, s[98:99]
	global_load_dwordx4 v[236:239], v[252:253], off
.LBB0_660:
	s_or_b64 exec, exec, s[16:17]
	v_lshl_add_u64 v[12:13], s[10:11], 0, v[0:1]
	global_load_dwordx4 v[6:9], v[12:13], off offset:128
	v_ashrrev_i32_e32 v15, 3, v14
	s_movk_i32 s10, 0xd0
	v_mul_lo_u32 v134, v15, s10
	v_add_u32_e32 v16, 0, v134
	v_add_u32_e32 v17, v16, v133
	v_mul_lo_u32 v135, v11, s10
	v_and_b32_e32 v136, 48, v10
	s_waitcnt vmcnt(0)
	ds_write_b128 v17, v[2:5]
	ds_write_b128 v17, v[248:251] offset:25600
	s_and_saveexec_b64 s[10:11], s[2:3]
	v_add3_u32 v2, 0, v135, v136
	ds_write_b128 v2, v[106:109] offset:128
	ds_write_b128 v2, v[236:239] offset:25728
	s_or_b64 exec, exec, s[10:11]
	v_lshlrev_b32_e32 v2, 4, v15
	v_sub_u32_e32 v2, v16, v2
	v_add_u32_e32 v2, v2, v133
	ds_write_b128 v2, v[6:9] offset:13312
	v_add_co_u32_e32 v2, vcc, 0x60000, v12
	v_mov_b32_e32 v11, v1
	s_nop 0
	v_addc_co_u32_e32 v3, vcc, 0, v13, vcc
	global_load_dwordx4 v[110:113], v[2:3], off
	s_and_saveexec_b64 s[10:11], s[4:5]
	s_xor_b64 s[4:5], exec, s[10:11]
	s_andn2_saveexec_b64 s[4:5], s[4:5]
	s_cbranch_execz .LBB0_664
	v_lshl_add_u64 v[2:3], s[8:9], 0, v[10:11]
	v_add_co_u32_e32 v2, vcc, 0x1800, v2
	s_nop 1
	v_addc_co_u32_e32 v3, vcc, 0, v3, vcc
	global_load_dwordx4 v[106:109], v[2:3], off
.LBB0_664:
	s_or_b64 exec, exec, s[4:5]
	v_add_co_u32_e32 v2, vcc, 0x40000, v12
	s_lshl_b32 s4, s18, 4
	s_nop 0
	v_addc_co_u32_e32 v3, vcc, 0, v13, vcc
	global_load_dwordx4 v[114:117], v[2:3], off offset:128
	s_and_b32 s8, s4, 0xf00
	v_readlane_b32 s4, v254, 0
	v_and_b32_e32 v2, 31, v14
	s_add_u32 s4, s4, s6
	v_readlane_b32 s5, v255, 14
	v_bfe_u32 v3, v14, 5, 1
	v_mul_u32_u24_e32 v138, 0xd0, v2
	v_bfe_u32 v2, v14, 2, 2
	s_addc_u32 s5, s5, s7
	v_lshl_or_b32 v2, v3, 2, v2
	s_add_u32 s0, s0, s8
	v_lshlrev_b32_e32 v139, 4, v3
	v_mul_u32_u24_e32 v140, 0xc0, v2
	v_and_b32_e32 v2, 16, v14
	v_lshlrev_b32_e32 v3, 2, v14
	s_addc_u32 s1, s1, 0
	v_and_or_b32 v2, v3, 12, v2
	s_add_u32 s0, s72, s0
	v_mul_lo_u32 v137, v15, s51
	v_lshlrev_b32_e32 v141, 1, v2
	v_lshl_add_u64 v[128:129], s[4:5], 0, v[10:11]
	s_mov_b32 s98, 0x800
	s_mov_b32 s99, 0
	v_lshl_add_u64 v[128:129], v[128:129], 0, s[98:99]
	s_addc_u32 s1, s73, s1
	v_mov_b32_e32 v2, v1
	v_mov_b32_e32 v3, v1
	v_mov_b32_e32 v4, v1
	v_mov_b32_e32 v5, v1
	v_mov_b32_e32 v6, v1
	v_mov_b32_e32 v7, v1
	v_mov_b32_e32 v8, v1
	v_mov_b32_e32 v9, v1
	v_mov_b32_e32 v10, v1
	v_mov_b32_e32 v11, v1
	v_mov_b32_e32 v12, v1
	v_mov_b32_e32 v13, v1
	v_mov_b32_e32 v14, v1
	v_mov_b32_e32 v15, v1
	v_mov_b32_e32 v16, v1
	v_mov_b32_e32 v17, v1
	v_mov_b32_e32 v18, v1
	v_mov_b32_e32 v19, v1
	v_mov_b32_e32 v20, v1
	v_mov_b32_e32 v21, v1
	v_mov_b32_e32 v22, v1
	v_mov_b32_e32 v23, v1
	v_mov_b32_e32 v24, v1
	v_mov_b32_e32 v25, v1
	v_mov_b32_e32 v26, v1
	v_mov_b32_e32 v27, v1
	v_mov_b32_e32 v28, v1
	v_mov_b32_e32 v29, v1
	v_mov_b32_e32 v30, v1
	v_mov_b32_e32 v31, v1
	v_lshl_add_u64 v[130:131], s[0:1], 0, v[0:1]
	v_mov_b32_e32 v0, v1
	v_mov_b32_e32 v143, 0
	v_mov_b64_e32 v[32:33], v[30:31]
	s_mov_b32 s10, 0
	s_mov_b64 s[0:1], 0
	v_mov_b32_e32 v142, 0
	v_mov_b64_e32 v[30:31], v[28:29]
	v_mov_b64_e32 v[28:29], v[26:27]
	v_mov_b64_e32 v[26:27], v[24:25]
	v_mov_b64_e32 v[24:25], v[22:23]
	v_mov_b64_e32 v[22:23], v[20:21]
	v_mov_b64_e32 v[20:21], v[18:19]
	v_mov_b64_e32 v[18:19], v[16:17]
	v_mov_b64_e32 v[16:17], v[14:15]
	v_mov_b64_e32 v[14:15], v[12:13]
	v_mov_b64_e32 v[12:13], v[10:11]
	v_mov_b64_e32 v[10:11], v[8:9]
	v_mov_b64_e32 v[8:9], v[6:7]
	v_mov_b64_e32 v[6:7], v[4:5]
	v_mov_b64_e32 v[4:5], v[2:3]
	v_mov_b64_e32 v[2:3], v[0:1]
	v_mov_b32_e32 v34, 0
	v_mov_b32_e32 v35, v143
	v_mov_b32_e32 v36, v143
	v_mov_b32_e32 v37, v143
	v_mov_b32_e32 v38, v143
	v_mov_b32_e32 v39, v143
	v_mov_b32_e32 v40, v143
	v_mov_b32_e32 v41, v143
	v_mov_b32_e32 v42, v143
	v_mov_b32_e32 v43, v143
	v_mov_b32_e32 v44, v143
	v_mov_b32_e32 v45, v143
	v_mov_b32_e32 v46, v143
	v_mov_b32_e32 v47, v143
	v_mov_b32_e32 v48, v143
	v_mov_b32_e32 v49, v143
	s_waitcnt lgkmcnt(0)
	s_barrier
	s_movk_i32 s8, 0x6400
	v_add3_u32 v239, s8, v138, v139
	ds_read_b128 v[182:185], v239 offset:6656
	ds_read_b128 v[186:189], v239 offset:6688
	ds_read_b128 v[190:193], v239 offset:6720
	ds_read_b128 v[202:205], v239 offset:6752
	ds_read_b128 v[206:209], v239 offset:6784
	ds_read_b128 v[210:213], v239 offset:6816
	s_setprio 1
	s_waitcnt lgkmcnt(5)
	v_mfma_f32_32x32x16_bf16 v[66:81], v[182:185], v[82:85], v[34:49]
	s_waitcnt lgkmcnt(4)
	v_mfma_f32_32x32x16_bf16 v[66:81], v[186:189], v[86:89], v[66:81]
	s_waitcnt lgkmcnt(3)
	v_mfma_f32_32x32x16_bf16 v[66:81], v[190:193], v[90:93], v[66:81]
	s_waitcnt lgkmcnt(2)
	v_mfma_f32_32x32x16_bf16 v[66:81], v[202:205], v[94:97], v[66:81]
	s_waitcnt lgkmcnt(1)
	v_mfma_f32_32x32x16_bf16 v[66:81], v[206:209], v[98:101], v[66:81]
	s_waitcnt lgkmcnt(0)
	v_mfma_f32_32x32x16_bf16 v[66:81], v[210:213], v[102:105], v[66:81]
	s_setprio 0
	s_nop 15
	v_max3_f32 v236, v66, v67, v68
	v_max3_f32 v237, v69, v70, v71
	v_max3_f32 v236, v236, v72, v73
	v_max3_f32 v237, v237, v74, v75
	v_max3_f32 v236, v236, v76, v77
	v_max3_f32 v237, v237, v78, v79
	v_max3_f32 v236, v236, v80, v81
	v_max_f32_e32 v236, v236, v237
	v_cmp_lt_f32_e64 s[100:101], s61, v236
.Lm_loop:
	s_and_b32 s11, s10, 1
	s_mul_i32 s8, s11, 0x6400
	v_add3_u32 v239, s8, v138, v139
	v_add_u32_e32 v240, s8, v140
	v_add_u32_e32 v240, v240, v141
	s_cmp_eq_u32 s0, 0
	s_cselect_b64 s[4:5], -1, 0
	s_cmp_lg_u32 s0, 0
	s_cselect_b64 s[6:7], -1, 0
	s_waitcnt lgkmcnt(0)
	s_barrier
	ds_read_b128 v[182:185], v239 offset:0
	ds_read_b128 v[186:189], v239 offset:32
	ds_read_b128 v[190:193], v239 offset:64
	ds_read_b128 v[202:205], v239 offset:96
	ds_read_b128 v[206:209], v239 offset:128
	ds_read_b128 v[210:213], v239 offset:160
	ds_read_b64_tr_b16 v[118:119], v240 offset:13312
	ds_read_b64_tr_b16 v[120:121], v240 offset:14848
	ds_read_b64_tr_b16 v[122:123], v240 offset:13376
	ds_read_b64_tr_b16 v[124:125], v240 offset:14912
	ds_read_b64_tr_b16 v[144:145], v240 offset:16384
	ds_read_b64_tr_b16 v[146:147], v240 offset:17920
	ds_read_b64_tr_b16 v[148:149], v240 offset:16448
	ds_read_b64_tr_b16 v[150:151], v240 offset:17984
	s_or_b64 s[16:17], s[100:101], s[4:5]
	s_cmp_lg_u64 s[16:17], 0
	s_cbranch_scc1 .Lm_rareA
.Lm_goA:
	s_setprio 1
	s_waitcnt lgkmcnt(13)
	v_mfma_f32_32x32x16_bf16 v[50:65], v[182:185], v[82:85], v[34:49]
	v_exp_f32_e32 v66, v66
	v_exp_f32_e32 v67, v67
	v_exp_f32_e32 v68, v68
	s_waitcnt lgkmcnt(12)
	v_mfma_f32_32x32x16_bf16 v[50:65], v[186:189], v[86:89], v[50:65]
	v_exp_f32_e32 v69, v69
	v_exp_f32_e32 v70, v70
	v_exp_f32_e32 v71, v71
	v_cvt_pk_bf16_f32 v152, v66, v67
	s_waitcnt lgkmcnt(11)
	v_mfma_f32_32x32x16_bf16 v[50:65], v[190:193], v[90:93], v[50:65]
	v_exp_f32_e32 v72, v72
	v_exp_f32_e32 v73, v73
	v_exp_f32_e32 v74, v74
	v_cvt_pk_bf16_f32 v153, v68, v69
	v_cvt_pk_bf16_f32 v154, v70, v71
	s_waitcnt lgkmcnt(10)
	v_mfma_f32_32x32x16_bf16 v[50:65], v[202:205], v[94:97], v[50:65]
	v_exp_f32_e32 v75, v75
	v_exp_f32_e32 v76, v76
	v_exp_f32_e32 v77, v77
	v_cvt_pk_bf16_f32 v155, v72, v73
	s_waitcnt lgkmcnt(9)
	v_mfma_f32_32x32x16_bf16 v[50:65], v[206:209], v[98:101], v[50:65]
	v_exp_f32_e32 v78, v78
	v_exp_f32_e32 v79, v79
	v_cvt_pk_bf16_f32 v214, v74, v75
	v_cvt_pk_bf16_f32 v215, v76, v77
	s_waitcnt lgkmcnt(8)
	v_mfma_f32_32x32x16_bf16 v[50:65], v[210:213], v[102:105], v[50:65]
	v_exp_f32_e32 v80, v80
	v_exp_f32_e32 v81, v81
	v_cvt_pk_bf16_f32 v216, v78, v79
	v_cvt_pk_bf16_f32 v217, v80, v81
	s_waitcnt lgkmcnt(6)
	v_mfma_f32_32x32x16_bf16 v[2:17], v[118:121], v[152:155], v[2:17]
	v_add_f32_e32 v218, v66, v68
	v_add_f32_e32 v219, v67, v69
	v_add_f32_e32 v218, v218, v70
	v_add_f32_e32 v219, v219, v71
	v_add_f32_e32 v218, v218, v72
	s_waitcnt lgkmcnt(4)
	v_mfma_f32_32x32x16_bf16 v[18:33], v[122:125], v[152:155], v[18:33]
	v_add_f32_e32 v219, v219, v73
	v_add_f32_e32 v218, v218, v74
	v_add_f32_e32 v219, v219, v75
	v_add_f32_e32 v218, v218, v76
	v_add_f32_e32 v219, v219, v77
	ds_read_b128 v[182:185], v239 offset:6656
	ds_read_b128 v[186:189], v239 offset:6688
	ds_read_b128 v[190:193], v239 offset:6720
	ds_read_b128 v[202:205], v239 offset:6752
	ds_read_b128 v[206:209], v239 offset:6784
	ds_read_b128 v[210:213], v239 offset:6816
	s_waitcnt lgkmcnt(8)
	v_mfma_f32_32x32x16_bf16 v[2:17], v[144:147], v[214:217], v[2:17]
	v_add_f32_e32 v218, v218, v78
	v_add_f32_e32 v219, v219, v79
	v_add_f32_e32 v218, v218, v80
	v_add_f32_e32 v219, v219, v81
	v_max3_f32 v236, v50, v51, v52
	v_max3_f32 v237, v53, v54, v55
	s_waitcnt lgkmcnt(6)
	v_mfma_f32_32x32x16_bf16 v[18:33], v[148:151], v[214:217], v[18:33]
	s_setprio 0
	v_max3_f32 v236, v236, v56, v57
	v_max3_f32 v237, v237, v58, v59
	v_max3_f32 v236, v236, v60, v61
	v_max3_f32 v237, v237, v62, v63
	v_max3_f32 v236, v236, v64, v65
	v_max_f32_e32 v236, v236, v237
	v_cmp_lt_f32_e64 s[100:101], s61, v236
	ds_read_b64_tr_b16 v[220:221], v240 offset:19456
	ds_read_b64_tr_b16 v[222:223], v240 offset:20992
	ds_read_b64_tr_b16 v[224:225], v240 offset:19520
	ds_read_b64_tr_b16 v[226:227], v240 offset:21056
	ds_read_b64_tr_b16 v[228:229], v240 offset:22528
	ds_read_b64_tr_b16 v[230:231], v240 offset:24064
	ds_read_b64_tr_b16 v[232:233], v240 offset:22592
	ds_read_b64_tr_b16 v[234:235], v240 offset:24128
	v_add_f32_e32 v218, v218, v219
	v_add_f32_e32 v142, v142, v218
	s_cmp_lg_u64 s[100:101], 0
	s_cbranch_scc1 .Lm_rareB
.Lm_goB:
	s_setprio 1
	s_waitcnt lgkmcnt(13)
	v_mfma_f32_32x32x16_bf16 v[66:81], v[182:185], v[82:85], v[34:49]
	v_exp_f32_e32 v50, v50
	v_exp_f32_e32 v51, v51
	v_exp_f32_e32 v52, v52
	s_waitcnt lgkmcnt(12)
	v_mfma_f32_32x32x16_bf16 v[66:81], v[186:189], v[86:89], v[66:81]
	v_exp_f32_e32 v53, v53
	v_exp_f32_e32 v54, v54
	v_exp_f32_e32 v55, v55
	v_cvt_pk_bf16_f32 v152, v50, v51
	s_waitcnt lgkmcnt(11)
	v_mfma_f32_32x32x16_bf16 v[66:81], v[190:193], v[90:93], v[66:81]
	v_exp_f32_e32 v56, v56
	v_exp_f32_e32 v57, v57
	v_exp_f32_e32 v58, v58
	v_cvt_pk_bf16_f32 v153, v52, v53
	v_cvt_pk_bf16_f32 v154, v54, v55
	s_waitcnt lgkmcnt(10)
	v_mfma_f32_32x32x16_bf16 v[66:81], v[202:205], v[94:97], v[66:81]
	v_exp_f32_e32 v59, v59
	v_exp_f32_e32 v60, v60
	v_exp_f32_e32 v61, v61
	v_cvt_pk_bf16_f32 v155, v56, v57
	s_waitcnt lgkmcnt(9)
	v_mfma_f32_32x32x16_bf16 v[66:81], v[206:209], v[98:101], v[66:81]
	v_exp_f32_e32 v62, v62
	v_exp_f32_e32 v63, v63
	v_cvt_pk_bf16_f32 v214, v58, v59
	v_cvt_pk_bf16_f32 v215, v60, v61
	s_waitcnt lgkmcnt(8)
	v_mfma_f32_32x32x16_bf16 v[66:81], v[210:213], v[102:105], v[66:81]
	v_exp_f32_e32 v64, v64
	v_exp_f32_e32 v65, v65
	v_cvt_pk_bf16_f32 v216, v62, v63
	v_cvt_pk_bf16_f32 v217, v64, v65
	s_waitcnt lgkmcnt(6)
	v_mfma_f32_32x32x16_bf16 v[2:17], v[220:223], v[152:155], v[2:17]
	v_add_f32_e32 v218, v50, v52
	v_add_f32_e32 v219, v51, v53
	v_add_f32_e32 v218, v218, v54
	v_add_f32_e32 v219, v219, v55
	v_add_f32_e32 v218, v218, v56
	s_waitcnt lgkmcnt(4)
	v_mfma_f32_32x32x16_bf16 v[18:33], v[224:227], v[152:155], v[18:33]
	v_add_f32_e32 v219, v219, v57
	v_add_f32_e32 v218, v218, v58
	v_add_f32_e32 v219, v219, v59
	v_add_f32_e32 v218, v218, v60
	v_add_f32_e32 v219, v219, v61
	s_waitcnt lgkmcnt(2)
	v_mfma_f32_32x32x16_bf16 v[2:17], v[228:231], v[214:217], v[2:17]
	v_add_f32_e32 v218, v218, v62
	v_add_f32_e32 v219, v219, v63
	v_add_f32_e32 v218, v218, v64
	v_add_f32_e32 v219, v219, v65
	v_max3_f32 v236, v66, v67, v68
	v_max3_f32 v237, v69, v70, v71
	s_waitcnt lgkmcnt(0)
	v_mfma_f32_32x32x16_bf16 v[18:33], v[232:235], v[214:217], v[18:33]
	s_setprio 0
	v_max3_f32 v236, v236, v72, v73
	v_max3_f32 v237, v237, v74, v75
	v_max3_f32 v236, v236, v76, v77
	v_max3_f32 v237, v237, v78, v79
	v_max3_f32 v236, v236, v80, v81
	v_max_f32_e32 v236, v236, v237
	v_cmp_lt_f32_e64 s[100:101], s61, v236
	v_add_f32_e32 v218, v218, v219
	v_add_f32_e32 v142, v142, v218
	s_cmp_eq_u32 s0, 0xfc0000
	s_cbranch_scc1 .Lm_next
	s_xor_b32 s4, s11, 1
	s_mulk_i32 s4, 0x6400
	s_mov_b32 s6, s4
	v_add3_u32 v241, s6, v134, v133
	s_waitcnt vmcnt(1)
	ds_write_b128 v241, v[110:113]
	s_and_saveexec_b64 s[4:5], s[2:3]
	v_add3_u32 v241, s6, v135, v136
	ds_write_b128 v241, v[106:109] offset:128
	s_or_b64 exec, exec, s[4:5]
	v_add3_u32 v241, s6, v137, v133
	s_cmp_gt_u32 s10, 61
	s_waitcnt vmcnt(0)
	ds_write_b128 v241, v[114:117] offset:13312
	s_cbranch_scc1 .Lm_next
	v_lshl_add_u64 v[242:243], v[130:131], 0, s[0:1]
	v_add_co_u32_e32 v110, vcc, 0x150a0000, v242
	s_nop 1
	v_addc_co_u32_e32 v111, vcc, 0, v243, vcc
	global_load_dwordx4 v[110:113], v[110:111], off
	s_and_saveexec_b64 s[4:5], s[2:3]
	s_cbranch_execz .Lm_nok2
	global_load_dwordx4 v[106:109], v[128:129], off
.Lm_nok2:
	s_or_b64 exec, exec, s[4:5]
	v_add_co_u32_e32 v242, vcc, 0x15080000, v242
	s_nop 1
	v_addc_co_u32_e32 v243, vcc, 0, v243, vcc
	global_load_dwordx4 v[114:117], v[242:243], off offset:128
.Lm_next:
	s_add_u32 s0, s0, 0x40000
	s_addc_u32 s1, s1, 0
	s_add_i32 s10, s10, 1
	s_cmp_lg_u32 s0, 0x1000000
	v_lshl_add_u64 v[128:129], v[128:129], 0, s[40:41]
	s_cbranch_scc1 .Lm_loop
	s_branch .LBB0_655
.Lm_rareA:
	s_nop 15
	v_mov_b32_e32 v238, v236
	s_nop 1
	v_permlane32_swap_b32_e32 v236, v238
	v_max_f32_e32 v238, v236, v238
	v_max_f32_e32 v34, v238, v238
	s_andn2_b64 vcc, exec, s[6:7]
	v_max_f32_e32 v34, 0, v34
	s_cbranch_vccnz .Lm_rareA2
	v_exp_f32_e64 v36, -v34
	s_nop 0
	v_mul_f32_e32 v142, v142, v36
	v_pk_mul_f32 v[32:33], v[32:33], v[36:37] op_sel_hi:[1,0]
	v_pk_mul_f32 v[30:31], v[30:31], v[36:37] op_sel_hi:[1,0]
	v_pk_mul_f32 v[28:29], v[28:29], v[36:37] op_sel_hi:[1,0]
	v_pk_mul_f32 v[26:27], v[26:27], v[36:37] op_sel_hi:[1,0]
	v_pk_mul_f32 v[24:25], v[24:25], v[36:37] op_sel_hi:[1,0]
	v_pk_mul_f32 v[22:23], v[22:23], v[36:37] op_sel_hi:[1,0]
	v_pk_mul_f32 v[20:21], v[20:21], v[36:37] op_sel_hi:[1,0]
	v_pk_mul_f32 v[18:19], v[18:19], v[36:37] op_sel_hi:[1,0]
	v_pk_mul_f32 v[16:17], v[16:17], v[36:37] op_sel_hi:[1,0]
	v_pk_mul_f32 v[14:15], v[14:15], v[36:37] op_sel_hi:[1,0]
	v_pk_mul_f32 v[12:13], v[12:13], v[36:37] op_sel_hi:[1,0]
	v_pk_mul_f32 v[10:11], v[10:11], v[36:37] op_sel_hi:[1,0]
	v_pk_mul_f32 v[8:9], v[8:9], v[36:37] op_sel_hi:[1,0]
	v_pk_mul_f32 v[6:7], v[6:7], v[36:37] op_sel_hi:[1,0]
	v_pk_mul_f32 v[4:5], v[4:5], v[36:37] op_sel_hi:[1,0]
	v_pk_mul_f32 v[2:3], v[2:3], v[36:37] op_sel_hi:[1,0]
.Lm_rareA2:
	v_cndmask_b32_e64 v34, v34, v238, s[4:5]
	v_add_f32_e32 v143, v143, v34
	v_xor_b32_e32 v49, 0x80000000, v143
	v_pk_add_f32 v[66:67], v[66:67], v[34:35] op_sel_hi:[1,0] neg_lo:[0,1] neg_hi:[0,1]
	v_pk_add_f32 v[68:69], v[68:69], v[34:35] op_sel_hi:[1,0] neg_lo:[0,1] neg_hi:[0,1]
	v_pk_add_f32 v[70:71], v[70:71], v[34:35] op_sel_hi:[1,0] neg_lo:[0,1] neg_hi:[0,1]
	v_pk_add_f32 v[72:73], v[72:73], v[34:35] op_sel_hi:[1,0] neg_lo:[0,1] neg_hi:[0,1]
	v_pk_add_f32 v[74:75], v[74:75], v[34:35] op_sel_hi:[1,0] neg_lo:[0,1] neg_hi:[0,1]
	v_pk_add_f32 v[76:77], v[76:77], v[34:35] op_sel_hi:[1,0] neg_lo:[0,1] neg_hi:[0,1]
	v_pk_add_f32 v[78:79], v[78:79], v[34:35] op_sel_hi:[1,0] neg_lo:[0,1] neg_hi:[0,1]
	v_pk_add_f32 v[80:81], v[80:81], v[34:35] op_sel_hi:[1,0] neg_lo:[0,1] neg_hi:[0,1]
	v_mov_b32_e32 v48, v49
	v_mov_b32_e32 v47, v49
	v_mov_b32_e32 v46, v49
	v_mov_b32_e32 v45, v49
	v_mov_b32_e32 v44, v49
	v_mov_b32_e32 v43, v49
	v_mov_b32_e32 v42, v49
	v_mov_b32_e32 v41, v49
	v_mov_b32_e32 v40, v49
	v_mov_b32_e32 v39, v49
	v_mov_b32_e32 v38, v49
	v_mov_b32_e32 v37, v49
	v_mov_b32_e32 v36, v49
	v_mov_b32_e32 v35, v49
	v_mov_b32_e32 v34, v49
	s_branch .Lm_goA
.Lm_rareB:
	s_nop 15
	v_mov_b32_e32 v238, v236
	s_nop 1
	v_permlane32_swap_b32_e32 v236, v238
	v_max_f32_e32 v238, v236, v238
	v_max_f32_e32 v34, v238, v238
	v_max_f32_e32 v34, 0, v34
	v_exp_f32_e64 v36, -v34
	s_nop 0
	v_mul_f32_e32 v142, v142, v36
	v_pk_mul_f32 v[32:33], v[32:33], v[36:37] op_sel_hi:[1,0]
	v_pk_mul_f32 v[30:31], v[30:31], v[36:37] op_sel_hi:[1,0]
	v_pk_mul_f32 v[28:29], v[28:29], v[36:37] op_sel_hi:[1,0]
	v_pk_mul_f32 v[26:27], v[26:27], v[36:37] op_sel_hi:[1,0]
	v_pk_mul_f32 v[24:25], v[24:25], v[36:37] op_sel_hi:[1,0]
	v_pk_mul_f32 v[22:23], v[22:23], v[36:37] op_sel_hi:[1,0]
	v_pk_mul_f32 v[20:21], v[20:21], v[36:37] op_sel_hi:[1,0]
	v_pk_mul_f32 v[18:19], v[18:19], v[36:37] op_sel_hi:[1,0]
	v_pk_mul_f32 v[16:17], v[16:17], v[36:37] op_sel_hi:[1,0]
	v_pk_mul_f32 v[14:15], v[14:15], v[36:37] op_sel_hi:[1,0]
	v_pk_mul_f32 v[12:13], v[12:13], v[36:37] op_sel_hi:[1,0]
	v_pk_mul_f32 v[10:11], v[10:11], v[36:37] op_sel_hi:[1,0]
	v_pk_mul_f32 v[8:9], v[8:9], v[36:37] op_sel_hi:[1,0]
	v_pk_mul_f32 v[6:7], v[6:7], v[36:37] op_sel_hi:[1,0]
	v_pk_mul_f32 v[4:5], v[4:5], v[36:37] op_sel_hi:[1,0]
	v_pk_mul_f32 v[2:3], v[2:3], v[36:37] op_sel_hi:[1,0]
	v_add_f32_e32 v143, v143, v34
	v_xor_b32_e32 v49, 0x80000000, v143
	v_pk_add_f32 v[50:51], v[50:51], v[34:35] op_sel_hi:[1,0] neg_lo:[0,1] neg_hi:[0,1]
	v_pk_add_f32 v[52:53], v[52:53], v[34:35] op_sel_hi:[1,0] neg_lo:[0,1] neg_hi:[0,1]
	v_pk_add_f32 v[54:55], v[54:55], v[34:35] op_sel_hi:[1,0] neg_lo:[0,1] neg_hi:[0,1]
	v_pk_add_f32 v[56:57], v[56:57], v[34:35] op_sel_hi:[1,0] neg_lo:[0,1] neg_hi:[0,1]
	v_pk_add_f32 v[58:59], v[58:59], v[34:35] op_sel_hi:[1,0] neg_lo:[0,1] neg_hi:[0,1]
	v_pk_add_f32 v[60:61], v[60:61], v[34:35] op_sel_hi:[1,0] neg_lo:[0,1] neg_hi:[0,1]
	v_pk_add_f32 v[62:63], v[62:63], v[34:35] op_sel_hi:[1,0] neg_lo:[0,1] neg_hi:[0,1]
	v_pk_add_f32 v[64:65], v[64:65], v[34:35] op_sel_hi:[1,0] neg_lo:[0,1] neg_hi:[0,1]
	v_mov_b32_e32 v48, v49
	v_mov_b32_e32 v47, v49
	v_mov_b32_e32 v46, v49
	v_mov_b32_e32 v45, v49
	v_mov_b32_e32 v44, v49
	v_mov_b32_e32 v43, v49
	v_mov_b32_e32 v42, v49
	v_mov_b32_e32 v41, v49
	v_mov_b32_e32 v40, v49
	v_mov_b32_e32 v39, v49
	v_mov_b32_e32 v38, v49
	v_mov_b32_e32 v37, v49
	v_mov_b32_e32 v36, v49
	v_mov_b32_e32 v35, v49
	v_mov_b32_e32 v34, v49
	s_branch .Lm_goB
